# fused epilogue row-statistics exchange: poll loop sleeps s_sleep 0 instead of s_sleep 2 between polls
# baseline (speedup 1.0000x reference)
.LBB0_554:
	v_mov_b64_e32 v[138:139], s[62:63]
	flat_load_dword v32, v[138:139] sc1
	s_waitcnt vmcnt(0) lgkmcnt(0)
	v_readfirstlane_b32 s28, v32
	s_cmp_gt_u32 s28, 31
	s_cbranch_scc1 .LBB0_552
	s_memrealtime s[50:51]
	s_mov_b64 s[52:53], -1
	s_mov_b64 s[64:65], -1
	s_waitcnt lgkmcnt(0)
	s_sub_u32 s50, s50, s46
	s_subb_u32 s51, s51, s47
	v_cmp_lt_u64_e32 vcc, s[50:51], v[180:181]
	s_cbranch_vccz .LBB0_553
	s_mov_b64 s[64:65], 0
	s_sleep 0
	s_branch .LBB0_553
